# rwkv_post: per-pass parameter loads issued together with the data loads (one round trip per pass instead of two)
# speedup vs baseline: 1.0017x; 1.0017x over previous
; __device__ __forceinline__ unsigned pk2(float lo, float hi) { const f32x2 v = {lo, hi}; const hwbf16x2 b = __builtin_convertvector(v, hwbf16x2); return __builtin_bit_cast(unsigned, b); }
; __device__ __forceinline__ void rwkv_post(const Args& a, int tid) {
;     ...
;     for (int row = gw; row < M; row += NGW) {
; #pragma unroll
;         for (int pass = 0; pass < 4; ++pass) {
;             const int c = (pass * 4 + grp) * 64 + 4 * sub;
;             const u32x2 yy = *(const u32x2*)(Y + (size_t)row * D + c);
;             const bf16* p = RK + (size_t)row * RW_N + c;
;             const u32x2 rr = *(const u32x2*)p, rk = *(const u32x2*)(p + 1024), rv = *(const u32x2*)(p + 2048);
;             const u32x2 gg = *(const u32x2*)(EA + (size_t)row * EA_LD + c), aa = *(const u32x2*)(EA + (size_t)row * EA_LD + 1024 + c);
;             const f32x4 y4 = (f32x4){bflo(yy.x), bfhi(yy.x), bflo(yy.y), bfhi(yy.y)};
;             const f32x4 r4 = (f32x4){bflo(rr.x), bfhi(rr.x), bflo(rr.y), bfhi(rr.y)}, k4 = (f32x4){bflo(rk.x), bfhi(rk.x), bflo(rk.y), bfhi(rk.y)};
;             const f32x4 v4 = (f32x4){bflo(rv.x), bfhi(rv.x), bflo(rv.y), bfhi(rv.y)}, g4 = (f32x4){bflo(gg.x), bfhi(gg.x), bflo(gg.y), bfhi(gg.y)};
;             const f32x4 a4 = (f32x4){bflo(aa.x), bfhi(aa.x), bflo(aa.y), bfhi(aa.y)};
;             const f32x4 kap = *(const f32x4*)(a.in[I_KA] + c), rkp = *(const f32x4*)(a.in[I_RK] + c), lw = *(const f32x4*)(a.in[I_LNW] + c), lb = *(const f32x4*)(a.in[I_LNB] + c);
;             const float mean = row16_sum((y4.x + y4.y) + (y4.z + y4.w)) * (1.f / 64.f);
;             const f32x4 d4 = y4 - mean;
;             const float var = row16_sum((d4.x * d4.x + d4.y * d4.y) + (d4.z * d4.z + d4.w * d4.w)) * (1.f / 64.f);
;             const float rstd = __builtin_amdgcn_rsqf(var + 64e-5f);
;             const f32x4 kt = k4 * ((a4 - 1.0f) * kap + 1.0f);
;             const f32x4 rkk = r4 * kt * rkp;
;             const float sd = row16_sum((rkk.x + rkk.y) + (rkk.z + rkk.w));
;             const f32x4 o = ((d4 * rstd) * lw + lb + v4 * sd) * g4;
;             u32x2 ov; ov.x = pk2(o.x, o.y); ov.y = pk2(o.z, o.w);
;             *(u32x2*)(Y + (size_t)row * D + c) = ov;
.LBB0_2367:
	v_lshl_add_u64 v[18:19], v[16:17], 0, v[2:3]
	v_add_co_u32_e32 v18, vcc, 0x19500000, v18
	v_lshl_add_u64 v[22:23], v[14:15], 0, v[2:3]
	s_nop 0
	v_addc_co_u32_e32 v19, vcc, 0, v19, vcc
	v_add_co_u32_e32 v20, vcc, 0xb500000, v22
	v_lshl_add_u64 v[24:25], v[12:13], 0, v[2:3]
	s_nop 0
	v_addc_co_u32_e32 v21, vcc, 0, v23, vcc
	v_add_co_u32_e32 v22, vcc, 0xb501000, v22
	global_load_dwordx2 v[42:43], v[18:19], off
	s_nop 0
	v_addc_co_u32_e32 v23, vcc, 0, v23, vcc
	v_add_co_u32_e32 v24, vcc, 0x3500000, v24
	global_load_dwordx2 v[26:27], v[20:21], off
	global_load_dwordx2 v[28:29], v[20:21], off offset:2048
	v_addc_co_u32_e32 v25, vcc, 0, v25, vcc
	global_load_dwordx2 v[30:31], v[22:23], off
	global_load_dwordx2 v[32:33], v[24:25], off
	global_load_dwordx2 v[34:35], v[24:25], off offset:2048
	global_load_dwordx4 v[100:103], v[4:5], off
	global_load_dwordx4 v[104:107], v[6:7], off
	global_load_dwordx4 v[108:111], v[8:9], off
	global_load_dwordx4 v[112:115], v[10:11], off
	v_add_u32_e32 v0, s14, v0
	v_cmp_lt_i32_e32 vcc, s12, v0
	v_lshl_add_u64 v[12:13], v[12:13], 0, s[2:3]
	v_lshl_add_u64 v[14:15], v[14:15], 0, s[4:5]
	v_lshl_add_u64 v[16:17], v[16:17], 0, s[6:7]
	s_or_b64 s[10:11], vcc, s[10:11]
	s_waitcnt vmcnt(9)
	v_lshlrev_b32_e32 v65, 16, v43
	v_lshlrev_b32_e32 v64, 16, v42
	v_and_b32_e32 v43, 0xffff0000, v43
	v_and_b32_e32 v42, 0xffff0000, v42
	s_waitcnt vmcnt(8)
	v_lshlrev_b32_e32 v44, 16, v26
	v_and_b32_e32 v45, 0xffff0000, v26
	v_lshlrev_b32_e32 v46, 16, v27
	v_and_b32_e32 v47, 0xffff0000, v27
	s_waitcnt vmcnt(7)
	v_lshlrev_b32_e32 v48, 16, v28
	v_and_b32_e32 v49, 0xffff0000, v28
	v_lshlrev_b32_e32 v50, 16, v29
	v_and_b32_e32 v51, 0xffff0000, v29
	s_waitcnt vmcnt(6)
	v_lshlrev_b32_e32 v52, 16, v30
	v_and_b32_e32 v53, 0xffff0000, v30
	v_lshlrev_b32_e32 v54, 16, v31
	v_and_b32_e32 v55, 0xffff0000, v31
	s_waitcnt vmcnt(5)
	v_lshlrev_b32_e32 v56, 16, v32
	v_and_b32_e32 v57, 0xffff0000, v32
	v_lshlrev_b32_e32 v58, 16, v33
	v_and_b32_e32 v59, 0xffff0000, v33
	s_waitcnt vmcnt(4)
	v_lshlrev_b32_e32 v60, 16, v34
	v_and_b32_e32 v61, 0xffff0000, v34
	v_lshlrev_b32_e32 v62, 16, v35
	v_and_b32_e32 v63, 0xffff0000, v35
	v_pk_add_f32 v[66:67], v[64:65], v[42:43]
	v_pk_add_f32 v[62:63], v[62:63], -1.0 op_sel_hi:[1,0]
	v_add_f32_e32 v66, v66, v67
	v_pk_add_f32 v[60:61], v[60:61], -1.0 op_sel_hi:[1,0]
	s_waitcnt vmcnt(3)
	v_pk_fma_f32 v[102:103], v[102:103], v[62:63], 1.0 op_sel_hi:[1,1,0]
	v_add_f32_dpp v66, v66, v66 quad_perm:[1,0,3,2] row_mask:0xf bank_mask:0xf bound_ctrl:1
	v_pk_fma_f32 v[100:101], v[100:101], v[60:61], 1.0 op_sel_hi:[1,1,0]
	v_pk_mul_f32 v[102:103], v[102:103], v[50:51]
	v_add_f32_dpp v66, v66, v66 quad_perm:[2,3,0,1] row_mask:0xf bank_mask:0xf bound_ctrl:1
	v_pk_mul_f32 v[100:101], v[100:101], v[48:49]
	v_pk_mul_f32 v[102:103], v[102:103], v[46:47]
	v_add_f32_dpp v66, v66, v66 row_half_mirror row_mask:0xf bank_mask:0xf bound_ctrl:1
	v_pk_mul_f32 v[100:101], v[100:101], v[44:45]
	s_waitcnt vmcnt(2)
	v_pk_mul_f32 v[102:103], v[106:107], v[102:103]
	v_add_f32_dpp v66, v66, v66 row_mirror row_mask:0xf bank_mask:0xf bound_ctrl:1
	v_fmac_f32_e32 v42, 0xbc800000, v66
	v_fmac_f32_e32 v43, 0xbc800000, v66
	v_fmac_f32_e32 v65, 0xbc800000, v66
	v_fmac_f32_e32 v64, 0xbc800000, v66
	v_mov_b32_e32 v66, v65
	v_mov_b32_e32 v67, v43
	v_mov_b32_e32 v65, v42
	v_pk_mul_f32 v[68:69], v[66:67], v[66:67]
	v_pk_mul_f32 v[42:43], v[64:65], v[64:65]
	v_pk_mul_f32 v[100:101], v[104:105], v[100:101]
	v_pk_mov_b32 v[70:71], v[42:43], v[68:69] op_sel:[1,0]
	v_mov_b32_e32 v43, v69
	v_pk_add_f32 v[42:43], v[70:71], v[42:43]
	v_pk_mov_b32 v[104:105], v[100:101], v[102:103] op_sel:[1,0]
	v_add_f32_e32 v42, v42, v43
	v_mov_b32_e32 v101, v103
	v_pk_add_f32 v[100:101], v[104:105], v[100:101]
	v_add_f32_dpp v42, v42, v42 quad_perm:[1,0,3,2] row_mask:0xf bank_mask:0xf bound_ctrl:1
	v_add_f32_e32 v100, v100, v101
	s_nop 0
	v_add_f32_dpp v42, v42, v42 quad_perm:[2,3,0,1] row_mask:0xf bank_mask:0xf bound_ctrl:1
	v_add_f32_dpp v100, v100, v100 quad_perm:[1,0,3,2] row_mask:0xf bank_mask:0xf bound_ctrl:1
	s_nop 0
	v_add_f32_dpp v42, v42, v42 row_half_mirror row_mask:0xf bank_mask:0xf bound_ctrl:1
	v_add_f32_dpp v100, v100, v100 quad_perm:[2,3,0,1] row_mask:0xf bank_mask:0xf bound_ctrl:1
	s_nop 0
	v_add_f32_dpp v42, v42, v42 row_mirror row_mask:0xf bank_mask:0xf bound_ctrl:1
	v_fmamk_f32 v42, v42, 0x3c800000, v1
	v_rsq_f32_e32 v42, v42
	v_add_f32_dpp v100, v100, v100 row_half_mirror row_mask:0xf bank_mask:0xf bound_ctrl:1
	v_pk_mul_f32 v[102:103], v[64:65], v[42:43] op_sel_hi:[1,0]
	v_pk_mul_f32 v[104:105], v[66:67], v[42:43] op_sel_hi:[1,0]
	v_add_f32_dpp v100, v100, v100 row_mirror row_mask:0xf bank_mask:0xf bound_ctrl:1
	s_waitcnt vmcnt(0)
	v_pk_fma_f32 v[104:105], v[110:111], v[104:105], v[114:115]
	v_pk_fma_f32 v[102:103], v[108:109], v[102:103], v[112:113]
	s_nop 0
	v_pk_fma_f32 v[102:103], v[100:101], v[52:53], v[102:103] op_sel_hi:[0,1,1]
	v_pk_fma_f32 v[100:101], v[100:101], v[54:55], v[104:105] op_sel_hi:[0,1,1]
	v_pk_mul_f32 v[100:101], v[100:101], v[58:59]
	v_pk_mul_f32 v[102:103], v[102:103], v[56:57]
	s_nop 0
	v_cvt_pk_bf16_f32 v102, v102, v103
	v_cvt_pk_bf16_f32 v103, v100, v101
	global_store_dwordx2 v[18:19], v[102:103], off
	global_load_dwordx2 v[42:43], v[18:19], off offset:512
	global_load_dwordx2 v[26:27], v[20:21], off offset:512
	s_nop 0
	global_load_dwordx2 v[28:29], v[20:21], off offset:2560
	global_load_dwordx2 v[30:31], v[22:23], off offset:512
	global_load_dwordx2 v[32:33], v[24:25], off offset:512
	global_load_dwordx2 v[34:35], v[24:25], off offset:2560
	global_load_dwordx4 v[100:103], v[4:5], off offset:1024
	global_load_dwordx4 v[104:107], v[6:7], off offset:1024
	global_load_dwordx4 v[108:111], v[8:9], off offset:1024
	global_load_dwordx4 v[112:115], v[10:11], off offset:1024
	s_waitcnt vmcnt(9)
; __device__ __forceinline__ unsigned pk2(float lo, float hi) { const f32x2 v = {lo, hi}; const hwbf16x2 b = __builtin_convertvector(v, hwbf16x2); return __builtin_bit_cast(unsigned, b); }
; __device__ __forceinline__ void rwkv_post(const Args& a, int tid) {
;     ...
;             const int c = (pass * 4 + grp) * 64 + 4 * sub;
;             const u32x2 yy = *(const u32x2*)(Y + (size_t)row * D + c);
;             const bf16* p = RK + (size_t)row * RW_N + c;
;             const u32x2 rr = *(const u32x2*)p, rk = *(const u32x2*)(p + 1024), rv = *(const u32x2*)(p + 2048);
;             const u32x2 gg = *(const u32x2*)(EA + (size_t)row * EA_LD + c), aa = *(const u32x2*)(EA + (size_t)row * EA_LD + 1024 + c);
;             const f32x4 y4 = (f32x4){bflo(yy.x), bfhi(yy.x), bflo(yy.y), bfhi(yy.y)};
;             const f32x4 r4 = (f32x4){bflo(rr.x), bfhi(rr.x), bflo(rr.y), bfhi(rr.y)}, k4 = (f32x4){bflo(rk.x), bfhi(rk.x), bflo(rk.y), bfhi(rk.y)};
;             const f32x4 v4 = (f32x4){bflo(rv.x), bfhi(rv.x), bflo(rv.y), bfhi(rv.y)}, g4 = (f32x4){bflo(gg.x), bfhi(gg.x), bflo(gg.y), bfhi(gg.y)};
;             const f32x4 a4 = (f32x4){bflo(aa.x), bfhi(aa.x), bflo(aa.y), bfhi(aa.y)};
;             const f32x4 kap = *(const f32x4*)(a.in[I_KA] + c), rkp = *(const f32x4*)(a.in[I_RK] + c), lw = *(const f32x4*)(a.in[I_LNW] + c), lb = *(const f32x4*)(a.in[I_LNB] + c);
;             const float mean = row16_sum((y4.x + y4.y) + (y4.z + y4.w)) * (1.f / 64.f);
;             const f32x4 d4 = y4 - mean;
;             const float var = row16_sum((d4.x * d4.x + d4.y * d4.y) + (d4.z * d4.z + d4.w * d4.w)) * (1.f / 64.f);
;             const float rstd = __builtin_amdgcn_rsqf(var + 64e-5f);
;             const f32x4 kt = k4 * ((a4 - 1.0f) * kap + 1.0f);
;             const f32x4 rkk = r4 * kt * rkp;
;             const float sd = row16_sum((rkk.x + rkk.y) + (rkk.z + rkk.w));
;             const f32x4 o = ((d4 * rstd) * lw + lb + v4 * sd) * g4;
;             u32x2 ov; ov.x = pk2(o.x, o.y); ov.y = pk2(o.z, o.w);
;             *(u32x2*)(Y + (size_t)row * D + c) = ov;
	v_lshlrev_b32_e32 v65, 16, v43
	s_waitcnt vmcnt(8)
	v_lshlrev_b32_e32 v44, 16, v26
	v_and_b32_e32 v45, 0xffff0000, v26
	v_lshlrev_b32_e32 v46, 16, v27
	v_and_b32_e32 v47, 0xffff0000, v27
	s_waitcnt vmcnt(7)
	v_lshlrev_b32_e32 v48, 16, v28
	v_and_b32_e32 v49, 0xffff0000, v28
	v_lshlrev_b32_e32 v50, 16, v29
	v_and_b32_e32 v51, 0xffff0000, v29
	s_waitcnt vmcnt(6)
	v_lshlrev_b32_e32 v52, 16, v30
	v_and_b32_e32 v53, 0xffff0000, v30
	v_lshlrev_b32_e32 v54, 16, v31
	v_and_b32_e32 v55, 0xffff0000, v31
	s_waitcnt vmcnt(5)
	v_lshlrev_b32_e32 v56, 16, v32
	v_and_b32_e32 v57, 0xffff0000, v32
	v_lshlrev_b32_e32 v58, 16, v33
	v_and_b32_e32 v59, 0xffff0000, v33
	s_waitcnt vmcnt(4)
	v_lshlrev_b32_e32 v60, 16, v34
	v_and_b32_e32 v61, 0xffff0000, v34
	v_lshlrev_b32_e32 v62, 16, v35
	v_and_b32_e32 v63, 0xffff0000, v35
	v_lshlrev_b32_e32 v64, 16, v42
	v_and_b32_e32 v43, 0xffff0000, v43
	v_and_b32_e32 v42, 0xffff0000, v42
	v_pk_add_f32 v[66:67], v[64:65], v[42:43]
	v_pk_add_f32 v[62:63], v[62:63], -1.0 op_sel_hi:[1,0]
	v_add_f32_e32 v66, v66, v67
	v_pk_add_f32 v[60:61], v[60:61], -1.0 op_sel_hi:[1,0]
	s_waitcnt vmcnt(3)
	v_pk_fma_f32 v[102:103], v[102:103], v[62:63], 1.0 op_sel_hi:[1,1,0]
	v_add_f32_dpp v66, v66, v66 quad_perm:[1,0,3,2] row_mask:0xf bank_mask:0xf bound_ctrl:1
	v_pk_fma_f32 v[100:101], v[100:101], v[60:61], 1.0 op_sel_hi:[1,1,0]
	v_pk_mul_f32 v[102:103], v[102:103], v[50:51]
	v_add_f32_dpp v66, v66, v66 quad_perm:[2,3,0,1] row_mask:0xf bank_mask:0xf bound_ctrl:1
	v_pk_mul_f32 v[100:101], v[100:101], v[48:49]
	v_pk_mul_f32 v[102:103], v[102:103], v[46:47]
	v_add_f32_dpp v66, v66, v66 row_half_mirror row_mask:0xf bank_mask:0xf bound_ctrl:1
	v_pk_mul_f32 v[100:101], v[100:101], v[44:45]
	s_waitcnt vmcnt(2)
	v_pk_mul_f32 v[102:103], v[106:107], v[102:103]
	v_add_f32_dpp v66, v66, v66 row_mirror row_mask:0xf bank_mask:0xf bound_ctrl:1
	v_fmac_f32_e32 v42, 0xbc800000, v66
	v_fmac_f32_e32 v43, 0xbc800000, v66
	v_fmac_f32_e32 v65, 0xbc800000, v66
	v_fmac_f32_e32 v64, 0xbc800000, v66
	v_mov_b32_e32 v66, v65
	v_mov_b32_e32 v67, v43
	v_mov_b32_e32 v65, v42
	v_pk_mul_f32 v[68:69], v[66:67], v[66:67]
	v_pk_mul_f32 v[42:43], v[64:65], v[64:65]
	v_pk_mul_f32 v[100:101], v[104:105], v[100:101]
	v_pk_mov_b32 v[70:71], v[42:43], v[68:69] op_sel:[1,0]
	v_mov_b32_e32 v43, v69
	v_pk_add_f32 v[42:43], v[70:71], v[42:43]
	v_pk_mov_b32 v[104:105], v[100:101], v[102:103] op_sel:[1,0]
	v_add_f32_e32 v42, v42, v43
	v_mov_b32_e32 v101, v103
	v_pk_add_f32 v[100:101], v[104:105], v[100:101]
	v_add_f32_dpp v42, v42, v42 quad_perm:[1,0,3,2] row_mask:0xf bank_mask:0xf bound_ctrl:1
	v_add_f32_e32 v100, v100, v101
	s_nop 0
	v_add_f32_dpp v42, v42, v42 quad_perm:[2,3,0,1] row_mask:0xf bank_mask:0xf bound_ctrl:1
	v_add_f32_dpp v100, v100, v100 quad_perm:[1,0,3,2] row_mask:0xf bank_mask:0xf bound_ctrl:1
	s_nop 0
	v_add_f32_dpp v42, v42, v42 row_half_mirror row_mask:0xf bank_mask:0xf bound_ctrl:1
	v_add_f32_dpp v100, v100, v100 quad_perm:[2,3,0,1] row_mask:0xf bank_mask:0xf bound_ctrl:1
	s_nop 0
	v_add_f32_dpp v42, v42, v42 row_mirror row_mask:0xf bank_mask:0xf bound_ctrl:1
	v_fmamk_f32 v42, v42, 0x3c800000, v1
	v_rsq_f32_e32 v42, v42
	v_add_f32_dpp v100, v100, v100 row_half_mirror row_mask:0xf bank_mask:0xf bound_ctrl:1
	v_pk_mul_f32 v[102:103], v[64:65], v[42:43] op_sel_hi:[1,0]
	v_pk_mul_f32 v[104:105], v[66:67], v[42:43] op_sel_hi:[1,0]
	v_add_f32_dpp v100, v100, v100 row_mirror row_mask:0xf bank_mask:0xf bound_ctrl:1
	s_waitcnt vmcnt(0)
	v_pk_fma_f32 v[104:105], v[110:111], v[104:105], v[114:115]
	v_pk_fma_f32 v[102:103], v[108:109], v[102:103], v[112:113]
	s_nop 0
	v_pk_fma_f32 v[102:103], v[100:101], v[52:53], v[102:103] op_sel_hi:[0,1,1]
	v_pk_fma_f32 v[100:101], v[100:101], v[54:55], v[104:105] op_sel_hi:[0,1,1]
	v_pk_mul_f32 v[100:101], v[100:101], v[58:59]
	v_pk_mul_f32 v[102:103], v[102:103], v[56:57]
	s_nop 0
	v_cvt_pk_bf16_f32 v102, v102, v103
	v_cvt_pk_bf16_f32 v103, v100, v101
	global_store_dwordx2 v[18:19], v[102:103], off offset:512
	global_load_dwordx2 v[42:43], v[18:19], off offset:1024
	global_load_dwordx2 v[26:27], v[20:21], off offset:1024
	s_nop 0
	global_load_dwordx2 v[28:29], v[20:21], off offset:3072
	global_load_dwordx2 v[30:31], v[22:23], off offset:1024
	global_load_dwordx2 v[32:33], v[24:25], off offset:1024
	global_load_dwordx2 v[34:35], v[24:25], off offset:3072
	global_load_dwordx4 v[100:103], v[4:5], off offset:2048
	global_load_dwordx4 v[104:107], v[6:7], off offset:2048
	global_load_dwordx4 v[108:111], v[8:9], off offset:2048
	global_load_dwordx4 v[112:115], v[10:11], off offset:2048
	s_waitcnt vmcnt(9)
	v_lshlrev_b32_e32 v65, 16, v43
	s_waitcnt vmcnt(8)
	v_lshlrev_b32_e32 v44, 16, v26
	v_and_b32_e32 v45, 0xffff0000, v26
	v_lshlrev_b32_e32 v46, 16, v27
	v_and_b32_e32 v47, 0xffff0000, v27
	s_waitcnt vmcnt(7)
	v_lshlrev_b32_e32 v48, 16, v28
	v_and_b32_e32 v49, 0xffff0000, v28
	v_lshlrev_b32_e32 v50, 16, v29
	v_and_b32_e32 v51, 0xffff0000, v29
	s_waitcnt vmcnt(6)
	v_lshlrev_b32_e32 v52, 16, v30
	v_and_b32_e32 v53, 0xffff0000, v30
	v_lshlrev_b32_e32 v54, 16, v31
	v_and_b32_e32 v55, 0xffff0000, v31
	s_waitcnt vmcnt(5)
	v_lshlrev_b32_e32 v56, 16, v32
	v_and_b32_e32 v57, 0xffff0000, v32
	v_lshlrev_b32_e32 v58, 16, v33
	v_and_b32_e32 v59, 0xffff0000, v33
	s_waitcnt vmcnt(4)
	v_lshlrev_b32_e32 v60, 16, v34
	v_and_b32_e32 v61, 0xffff0000, v34
	v_lshlrev_b32_e32 v62, 16, v35
	v_and_b32_e32 v63, 0xffff0000, v35
	v_lshlrev_b32_e32 v64, 16, v42
	v_and_b32_e32 v43, 0xffff0000, v43
	v_and_b32_e32 v42, 0xffff0000, v42
	v_pk_add_f32 v[66:67], v[64:65], v[42:43]
	v_pk_add_f32 v[62:63], v[62:63], -1.0 op_sel_hi:[1,0]
	v_add_f32_e32 v66, v66, v67
	v_pk_add_f32 v[60:61], v[60:61], -1.0 op_sel_hi:[1,0]
	s_waitcnt vmcnt(3)
; __device__ __forceinline__ unsigned pk2(float lo, float hi) { const f32x2 v = {lo, hi}; const hwbf16x2 b = __builtin_convertvector(v, hwbf16x2); return __builtin_bit_cast(unsigned, b); }
; __device__ __forceinline__ void rwkv_post(const Args& a, int tid) {
;     ...
;             const int c = (pass * 4 + grp) * 64 + 4 * sub;
;             const u32x2 yy = *(const u32x2*)(Y + (size_t)row * D + c);
;             const bf16* p = RK + (size_t)row * RW_N + c;
;             const u32x2 rr = *(const u32x2*)p, rk = *(const u32x2*)(p + 1024), rv = *(const u32x2*)(p + 2048);
;             const u32x2 gg = *(const u32x2*)(EA + (size_t)row * EA_LD + c), aa = *(const u32x2*)(EA + (size_t)row * EA_LD + 1024 + c);
;             const f32x4 y4 = (f32x4){bflo(yy.x), bfhi(yy.x), bflo(yy.y), bfhi(yy.y)};
;             const f32x4 r4 = (f32x4){bflo(rr.x), bfhi(rr.x), bflo(rr.y), bfhi(rr.y)}, k4 = (f32x4){bflo(rk.x), bfhi(rk.x), bflo(rk.y), bfhi(rk.y)};
;             const f32x4 v4 = (f32x4){bflo(rv.x), bfhi(rv.x), bflo(rv.y), bfhi(rv.y)}, g4 = (f32x4){bflo(gg.x), bfhi(gg.x), bflo(gg.y), bfhi(gg.y)};
;             const f32x4 a4 = (f32x4){bflo(aa.x), bfhi(aa.x), bflo(aa.y), bfhi(aa.y)};
;             const f32x4 kap = *(const f32x4*)(a.in[I_KA] + c), rkp = *(const f32x4*)(a.in[I_RK] + c), lw = *(const f32x4*)(a.in[I_LNW] + c), lb = *(const f32x4*)(a.in[I_LNB] + c);
;             const float mean = row16_sum((y4.x + y4.y) + (y4.z + y4.w)) * (1.f / 64.f);
;             const f32x4 d4 = y4 - mean;
;             const float var = row16_sum((d4.x * d4.x + d4.y * d4.y) + (d4.z * d4.z + d4.w * d4.w)) * (1.f / 64.f);
;             const float rstd = __builtin_amdgcn_rsqf(var + 64e-5f);
;             const f32x4 kt = k4 * ((a4 - 1.0f) * kap + 1.0f);
;             const f32x4 rkk = r4 * kt * rkp;
;             const float sd = row16_sum((rkk.x + rkk.y) + (rkk.z + rkk.w));
;             const f32x4 o = ((d4 * rstd) * lw + lb + v4 * sd) * g4;
;             u32x2 ov; ov.x = pk2(o.x, o.y); ov.y = pk2(o.z, o.w);
;             *(u32x2*)(Y + (size_t)row * D + c) = ov;
	v_pk_fma_f32 v[102:103], v[102:103], v[62:63], 1.0 op_sel_hi:[1,1,0]
	v_add_f32_dpp v66, v66, v66 quad_perm:[1,0,3,2] row_mask:0xf bank_mask:0xf bound_ctrl:1
	v_pk_fma_f32 v[100:101], v[100:101], v[60:61], 1.0 op_sel_hi:[1,1,0]
	v_pk_mul_f32 v[102:103], v[102:103], v[50:51]
	v_add_f32_dpp v66, v66, v66 quad_perm:[2,3,0,1] row_mask:0xf bank_mask:0xf bound_ctrl:1
	v_pk_mul_f32 v[100:101], v[100:101], v[48:49]
	v_pk_mul_f32 v[102:103], v[102:103], v[46:47]
	v_add_f32_dpp v66, v66, v66 row_half_mirror row_mask:0xf bank_mask:0xf bound_ctrl:1
	v_pk_mul_f32 v[100:101], v[100:101], v[44:45]
	s_waitcnt vmcnt(2)
	v_pk_mul_f32 v[102:103], v[106:107], v[102:103]
	v_add_f32_dpp v66, v66, v66 row_mirror row_mask:0xf bank_mask:0xf bound_ctrl:1
	v_fmac_f32_e32 v42, 0xbc800000, v66
	v_fmac_f32_e32 v43, 0xbc800000, v66
	v_fmac_f32_e32 v65, 0xbc800000, v66
	v_fmac_f32_e32 v64, 0xbc800000, v66
	v_mov_b32_e32 v66, v65
	v_mov_b32_e32 v67, v43
	v_mov_b32_e32 v65, v42
	v_pk_mul_f32 v[68:69], v[66:67], v[66:67]
	v_pk_mul_f32 v[42:43], v[64:65], v[64:65]
	v_pk_mul_f32 v[100:101], v[104:105], v[100:101]
	v_pk_mov_b32 v[70:71], v[42:43], v[68:69] op_sel:[1,0]
	v_mov_b32_e32 v43, v69
	v_pk_add_f32 v[42:43], v[70:71], v[42:43]
	v_pk_mov_b32 v[104:105], v[100:101], v[102:103] op_sel:[1,0]
	v_add_f32_e32 v42, v42, v43
	v_mov_b32_e32 v101, v103
	v_pk_add_f32 v[100:101], v[104:105], v[100:101]
	v_add_f32_dpp v42, v42, v42 quad_perm:[1,0,3,2] row_mask:0xf bank_mask:0xf bound_ctrl:1
	v_add_f32_e32 v100, v100, v101
	s_nop 0
	v_add_f32_dpp v42, v42, v42 quad_perm:[2,3,0,1] row_mask:0xf bank_mask:0xf bound_ctrl:1
	v_add_f32_dpp v100, v100, v100 quad_perm:[1,0,3,2] row_mask:0xf bank_mask:0xf bound_ctrl:1
	s_nop 0
	v_add_f32_dpp v42, v42, v42 row_half_mirror row_mask:0xf bank_mask:0xf bound_ctrl:1
	v_add_f32_dpp v100, v100, v100 quad_perm:[2,3,0,1] row_mask:0xf bank_mask:0xf bound_ctrl:1
	s_nop 0
	v_add_f32_dpp v42, v42, v42 row_mirror row_mask:0xf bank_mask:0xf bound_ctrl:1
	v_fmamk_f32 v42, v42, 0x3c800000, v1
	v_rsq_f32_e32 v42, v42
	v_add_f32_dpp v100, v100, v100 row_half_mirror row_mask:0xf bank_mask:0xf bound_ctrl:1
	v_pk_mul_f32 v[102:103], v[64:65], v[42:43] op_sel_hi:[1,0]
	v_pk_mul_f32 v[104:105], v[66:67], v[42:43] op_sel_hi:[1,0]
	v_add_f32_dpp v100, v100, v100 row_mirror row_mask:0xf bank_mask:0xf bound_ctrl:1
	s_waitcnt vmcnt(0)
	v_pk_fma_f32 v[104:105], v[110:111], v[104:105], v[114:115]
	v_pk_fma_f32 v[102:103], v[108:109], v[102:103], v[112:113]
	s_nop 0
	v_pk_fma_f32 v[102:103], v[100:101], v[52:53], v[102:103] op_sel_hi:[0,1,1]
	v_pk_fma_f32 v[100:101], v[100:101], v[54:55], v[104:105] op_sel_hi:[0,1,1]
	v_pk_mul_f32 v[100:101], v[100:101], v[58:59]
	v_pk_mul_f32 v[102:103], v[102:103], v[56:57]
	s_nop 0
	v_cvt_pk_bf16_f32 v102, v102, v103
	v_cvt_pk_bf16_f32 v103, v100, v101
	global_store_dwordx2 v[18:19], v[102:103], off offset:1024
	global_load_dwordx2 v[36:37], v[18:19], off offset:1536
	global_load_dwordx2 v[26:27], v[20:21], off offset:1536
	s_nop 0
	global_load_dwordx2 v[20:21], v[20:21], off offset:3584
	s_nop 0
	global_load_dwordx2 v[22:23], v[22:23], off offset:1536
	s_nop 0
	global_load_dwordx2 v[28:29], v[24:25], off offset:1536
	s_nop 0
	global_load_dwordx2 v[24:25], v[24:25], off offset:3584
	global_load_dwordx4 v[100:103], v[4:5], off offset:3072
	global_load_dwordx4 v[104:107], v[6:7], off offset:3072
	global_load_dwordx4 v[108:111], v[8:9], off offset:3072
	global_load_dwordx4 v[112:115], v[10:11], off offset:3072
	s_waitcnt vmcnt(9)
	v_lshlrev_b32_e32 v59, 16, v37
	s_waitcnt vmcnt(8)
	v_lshlrev_b32_e32 v38, 16, v26
	v_and_b32_e32 v39, 0xffff0000, v26
	v_lshlrev_b32_e32 v40, 16, v27
	v_and_b32_e32 v41, 0xffff0000, v27
	s_waitcnt vmcnt(7)
; __device__ __forceinline__ unsigned pk2(float lo, float hi) { const f32x2 v = {lo, hi}; const hwbf16x2 b = __builtin_convertvector(v, hwbf16x2); return __builtin_bit_cast(unsigned, b); }
; __device__ __forceinline__ void rwkv_post(const Args& a, int tid) {
;     ...
;             const int c = (pass * 4 + grp) * 64 + 4 * sub;
;             const u32x2 yy = *(const u32x2*)(Y + (size_t)row * D + c);
;             const bf16* p = RK + (size_t)row * RW_N + c;
;             const u32x2 rr = *(const u32x2*)p, rk = *(const u32x2*)(p + 1024), rv = *(const u32x2*)(p + 2048);
;             const u32x2 gg = *(const u32x2*)(EA + (size_t)row * EA_LD + c), aa = *(const u32x2*)(EA + (size_t)row * EA_LD + 1024 + c);
;             const f32x4 y4 = (f32x4){bflo(yy.x), bfhi(yy.x), bflo(yy.y), bfhi(yy.y)};
;             const f32x4 r4 = (f32x4){bflo(rr.x), bfhi(rr.x), bflo(rr.y), bfhi(rr.y)}, k4 = (f32x4){bflo(rk.x), bfhi(rk.x), bflo(rk.y), bfhi(rk.y)};
;             const f32x4 v4 = (f32x4){bflo(rv.x), bfhi(rv.x), bflo(rv.y), bfhi(rv.y)}, g4 = (f32x4){bflo(gg.x), bfhi(gg.x), bflo(gg.y), bfhi(gg.y)};
;             const f32x4 a4 = (f32x4){bflo(aa.x), bfhi(aa.x), bflo(aa.y), bfhi(aa.y)};
;             const f32x4 kap = *(const f32x4*)(a.in[I_KA] + c), rkp = *(const f32x4*)(a.in[I_RK] + c), lw = *(const f32x4*)(a.in[I_LNW] + c), lb = *(const f32x4*)(a.in[I_LNB] + c);
;             const float mean = row16_sum((y4.x + y4.y) + (y4.z + y4.w)) * (1.f / 64.f);
;             const f32x4 d4 = y4 - mean;
;             const float var = row16_sum((d4.x * d4.x + d4.y * d4.y) + (d4.z * d4.z + d4.w * d4.w)) * (1.f / 64.f);
;             const float rstd = __builtin_amdgcn_rsqf(var + 64e-5f);
;             const f32x4 kt = k4 * ((a4 - 1.0f) * kap + 1.0f);
;             const f32x4 rkk = r4 * kt * rkp;
;             const float sd = row16_sum((rkk.x + rkk.y) + (rkk.z + rkk.w));
;             const f32x4 o = ((d4 * rstd) * lw + lb + v4 * sd) * g4;
;             u32x2 ov; ov.x = pk2(o.x, o.y); ov.y = pk2(o.z, o.w);
;             *(u32x2*)(Y + (size_t)row * D + c) = ov;
;         }
;     }
	v_lshlrev_b32_e32 v42, 16, v20
	v_and_b32_e32 v43, 0xffff0000, v20
	v_lshlrev_b32_e32 v44, 16, v21
	v_and_b32_e32 v45, 0xffff0000, v21
	s_waitcnt vmcnt(6)
	v_lshlrev_b32_e32 v46, 16, v22
	v_and_b32_e32 v47, 0xffff0000, v22
	v_lshlrev_b32_e32 v48, 16, v23
	v_and_b32_e32 v49, 0xffff0000, v23
	s_waitcnt vmcnt(5)
	v_lshlrev_b32_e32 v50, 16, v28
	v_and_b32_e32 v51, 0xffff0000, v28
	v_lshlrev_b32_e32 v52, 16, v29
	v_and_b32_e32 v53, 0xffff0000, v29
	s_waitcnt vmcnt(4)
	v_lshlrev_b32_e32 v54, 16, v24
	v_and_b32_e32 v55, 0xffff0000, v24
	v_lshlrev_b32_e32 v56, 16, v25
	v_and_b32_e32 v57, 0xffff0000, v25
	v_lshlrev_b32_e32 v58, 16, v36
	v_and_b32_e32 v37, 0xffff0000, v37
	v_and_b32_e32 v36, 0xffff0000, v36
	v_pk_add_f32 v[60:61], v[58:59], v[36:37]
	v_pk_add_f32 v[56:57], v[56:57], -1.0 op_sel_hi:[1,0]
	v_add_f32_e32 v60, v60, v61
	v_pk_add_f32 v[54:55], v[54:55], -1.0 op_sel_hi:[1,0]
	s_waitcnt vmcnt(3)
	v_pk_fma_f32 v[102:103], v[102:103], v[56:57], 1.0 op_sel_hi:[1,1,0]
	v_add_f32_dpp v60, v60, v60 quad_perm:[1,0,3,2] row_mask:0xf bank_mask:0xf bound_ctrl:1
	v_pk_fma_f32 v[100:101], v[100:101], v[54:55], 1.0 op_sel_hi:[1,1,0]
	v_pk_mul_f32 v[102:103], v[102:103], v[44:45]
	v_add_f32_dpp v60, v60, v60 quad_perm:[2,3,0,1] row_mask:0xf bank_mask:0xf bound_ctrl:1
	v_pk_mul_f32 v[100:101], v[100:101], v[42:43]
	v_pk_mul_f32 v[102:103], v[102:103], v[40:41]
	v_add_f32_dpp v60, v60, v60 row_half_mirror row_mask:0xf bank_mask:0xf bound_ctrl:1
	v_pk_mul_f32 v[100:101], v[100:101], v[38:39]
	s_waitcnt vmcnt(2)
	v_pk_mul_f32 v[102:103], v[106:107], v[102:103]
	v_add_f32_dpp v60, v60, v60 row_mirror row_mask:0xf bank_mask:0xf bound_ctrl:1
	v_fmac_f32_e32 v36, 0xbc800000, v60
	v_fmac_f32_e32 v37, 0xbc800000, v60
	v_fmac_f32_e32 v59, 0xbc800000, v60
	v_fmac_f32_e32 v58, 0xbc800000, v60
	v_mov_b32_e32 v60, v59
	v_mov_b32_e32 v61, v37
	v_mov_b32_e32 v59, v36
	v_pk_mul_f32 v[62:63], v[60:61], v[60:61]
	v_pk_mul_f32 v[36:37], v[58:59], v[58:59]
	v_pk_mul_f32 v[100:101], v[104:105], v[100:101]
	v_pk_mov_b32 v[64:65], v[36:37], v[62:63] op_sel:[1,0]
	v_mov_b32_e32 v37, v63
	v_pk_add_f32 v[36:37], v[64:65], v[36:37]
	v_pk_mov_b32 v[104:105], v[100:101], v[102:103] op_sel:[1,0]
	v_add_f32_e32 v36, v36, v37
	v_mov_b32_e32 v101, v103
	v_pk_add_f32 v[100:101], v[104:105], v[100:101]
	v_add_f32_dpp v36, v36, v36 quad_perm:[1,0,3,2] row_mask:0xf bank_mask:0xf bound_ctrl:1
	v_add_f32_e32 v100, v100, v101
	s_nop 0
	v_add_f32_dpp v36, v36, v36 quad_perm:[2,3,0,1] row_mask:0xf bank_mask:0xf bound_ctrl:1
	v_add_f32_dpp v100, v100, v100 quad_perm:[1,0,3,2] row_mask:0xf bank_mask:0xf bound_ctrl:1
	s_nop 0
	v_add_f32_dpp v36, v36, v36 row_half_mirror row_mask:0xf bank_mask:0xf bound_ctrl:1
	v_add_f32_dpp v100, v100, v100 quad_perm:[2,3,0,1] row_mask:0xf bank_mask:0xf bound_ctrl:1
	s_nop 0
	v_add_f32_dpp v36, v36, v36 row_mirror row_mask:0xf bank_mask:0xf bound_ctrl:1
	v_fmamk_f32 v36, v36, 0x3c800000, v1
	v_rsq_f32_e32 v36, v36
	v_add_f32_dpp v100, v100, v100 row_half_mirror row_mask:0xf bank_mask:0xf bound_ctrl:1
	v_pk_mul_f32 v[102:103], v[58:59], v[36:37] op_sel_hi:[1,0]
	v_pk_mul_f32 v[104:105], v[60:61], v[36:37] op_sel_hi:[1,0]
	v_add_f32_dpp v100, v100, v100 row_mirror row_mask:0xf bank_mask:0xf bound_ctrl:1
	s_waitcnt vmcnt(0)
	v_pk_fma_f32 v[104:105], v[110:111], v[104:105], v[114:115]
	v_pk_fma_f32 v[102:103], v[108:109], v[102:103], v[112:113]
	s_nop 0
	v_pk_fma_f32 v[102:103], v[100:101], v[46:47], v[102:103] op_sel_hi:[0,1,1]
	v_pk_fma_f32 v[100:101], v[100:101], v[48:49], v[104:105] op_sel_hi:[0,1,1]
	v_pk_mul_f32 v[100:101], v[100:101], v[52:53]
	v_pk_mul_f32 v[102:103], v[102:103], v[50:51]
	s_nop 0
	v_cvt_pk_bf16_f32 v102, v102, v103
	v_cvt_pk_bf16_f32 v103, v100, v101
	global_store_dwordx2 v[18:19], v[102:103], off offset:1536
	s_andn2_b64 exec, exec, s[10:11]
	s_cbranch_execnz .LBB0_2367
